# grid-barrier spin loop polls without s_sleep (s_nop 0 instead of s_sleep 1)
# baseline (speedup 1.0000x reference)
; DI void grid_barrier(unsigned* ctr, unsigned target) {
;   asm volatile("s_waitcnt vmcnt(0)" ::: "memory");
;   __syncthreads();
;   if (threadIdx.x == 0) {
;     __builtin_amdgcn_fence(__ATOMIC_RELEASE, "agent");
;     asm volatile("s_waitcnt vmcnt(0)" ::: "memory");
;     __hip_atomic_fetch_add(ctr, 1u, __ATOMIC_RELAXED, __HIP_MEMORY_SCOPE_AGENT);
;     while (__hip_atomic_load(ctr, __ATOMIC_RELAXED, __HIP_MEMORY_SCOPE_AGENT) < target) __builtin_amdgcn_s_sleep(1);
;     __builtin_amdgcn_fence(__ATOMIC_ACQUIRE, "agent");
;     asm volatile("s_waitcnt vmcnt(0)" ::: "memory");
;   }
.LBB0_16:
	s_nop 0
	global_load_dword v0, v1, s[72:73] sc1
	s_waitcnt vmcnt(0)
	v_cmp_gt_u32_e32 vcc, s8, v0
	s_cbranch_vccnz .LBB0_16
